# attention output rows: v_permlane32_swap pairs + 4 global_store_dwordx4 per unit instead of 8 interleaved global_store_dwordx2
# baseline (speedup 1.0000x reference)
.LBB0_782:
	s_and_b32 s5, s19, 0xe00
	s_add_i32 s16, s18, s5
	s_pack_ll_b32_b16 s5, s4, s4
	s_or_b32 s5, s5, 0x1c00180
	s_and_b32 s10, s5, 0xfff
	s_mulk_i32 s10, 0xaab
	s_lshr_b32 s10, s10, 20
	s_mulk_i32 s10, 0x180
	s_sub_i32 s10, s5, s10
	s_and_b32 s10, s10, 0xffff
	v_add_u32_e32 v1, s10, v120
	v_lshlrev_b32_e32 v28, 7, v1
	v_lshrrev_b32_e32 v1, 1, v1
	s_lshr_b32 s5, s5, 16
	v_xor_b32_e32 v1, v1, v115
	s_mul_i32 s17, s5, 0xaab
	v_lshlrev_b32_e32 v1, 4, v1
	s_lshr_b32 s17, s17, 20
	v_and_b32_e32 v1, 0x70, v1
	s_mulk_i32 s17, 0x180
	v_add3_u32 v1, 0, v28, v1
	s_sub_i32 s5, s5, s17
	s_waitcnt vmcnt(1)
	ds_write_b128 v1, v[22:25]
	v_or_b32_e32 v1, s10, v110
	s_and_b32 s5, s5, 0xffff
	v_lshlrev_b32_e32 v1, 1, v1
	v_add_u32_e32 v26, s5, v111
	v_add3_u32 v1, v121, v1, s21
	ds_write2_b64 v1, v[14:15], v[16:17] offset1:1
	v_lshrrev_b32_e32 v1, 1, v26
	v_xor_b32_e32 v1, v1, v115
	v_lshlrev_b32_e32 v1, 4, v1
	v_lshlrev_b32_e32 v27, 7, v26
	v_and_b32_e32 v1, 0x70, v1
	v_add3_u32 v1, 0, v27, v1
	s_addk_i32 s4, 0x200
	ds_write_b128 v1, v[18:21]
	v_or_b32_e32 v1, s5, v110
	s_and_b32 s5, s4, 0x1fff
	s_mulk_i32 s5, 0xaab
	s_lshr_b32 s5, s5, 20
	s_mulk_i32 s5, 0x180
	v_lshlrev_b32_e32 v1, 1, v1
	s_sub_i32 s4, s4, s5
	v_add3_u32 v1, v121, v1, s21
	s_and_b32 s4, s4, 0xffff
	ds_write2_b64 v1, v[10:11], v[12:13] offset1:1
	v_add_u32_e32 v1, s4, v108
	v_lshlrev_b32_e32 v10, 7, v1
	v_lshrrev_b32_e32 v1, 1, v1
	v_xor_b32_e32 v1, v1, v115
	v_lshlrev_b32_e32 v1, 4, v1
	v_and_b32_e32 v1, 0x70, v1
	v_add3_u32 v1, 0, v10, v1
	ds_write_b128 v1, v[6:9]
	v_or_b32_e32 v1, s4, v110
	s_lshl_b32 s4, s24, 2
	s_or_b32 s4, s4, s0
	s_lshl_b32 s10, s4, 7
	s_lshl_b32 s4, s4, 2
	v_lshlrev_b32_e32 v1, 1, v1
	v_or_b32_e32 v130, s14, v114
	s_add_u32 s14, s48, s4
	v_add3_u32 v1, v121, v1, s21
	v_mov_b32_e32 v131, s15
	v_lshl_add_u64 v[134:135], v[116:117], 0, s[10:11]
	s_addc_u32 s15, s49, 0
	v_lshl_add_u64 v[136:137], v[118:119], 0, s[10:11]
	s_waitcnt vmcnt(0)
	ds_write2_b64 v1, v[2:3], v[4:5] offset1:1
	s_waitcnt lgkmcnt(0)
	s_barrier
	s_add_i32 s10, s12, s1
	v_lshl_add_u64 v[186:187], v[130:131], 0, s[10:11]
	v_lshlrev_b64 v[186:187], 11, v[186:187]
	v_lshl_add_u64 v[186:187], v[186:187], 1, v[134:135]
	v_mov_b32_e32 v189, 0
	global_load_dwordx4 v[170:173], v[186:187], off
	global_load_dwordx4 v[174:177], v[186:187], off offset:32
	global_load_dwordx4 v[178:181], v[186:187], off offset:64
	global_load_dwordx4 v[182:185], v[186:187], off offset:96
	global_load_dword v188, v189, s[14:15]
	s_waitcnt vmcnt(0)
	v_mul_f32_e32 v188, 0x3fb8aa3b, v188
	v_mbcnt_lo_u32_b32 v249, -1, 0
	v_mbcnt_hi_u32_b32 v249, -1, v249
	v_and_b32_e32 v251, 3, v249
	v_lshrrev_b32_e32 v250, 4, v249
	v_lshlrev_b32_e32 v250, 5, v250
	v_lshl_or_b32 v250, v251, 3, v250
	v_bfe_u32 v252, v249, 3, 1
	v_lshl_or_b32 v250, v252, 2, v250
	v_lshlrev_b32_e32 v251, 2, v251
	v_lshlrev_b32_e32 v249, 4, v249
	v_mov_b32_e32 v252, 0
	v_lshrrev_b32_e32 v254, 9, v249
	v_mul_u32_u24_e32 v254, 24, v254
	v_mov_b32_e32 v255, 0
	v_readlane_b32 s86, v248, 0
	s_lshr_b32 s86, s86, 6
	s_lshl_b32 s94, s2, 3
	s_add_i32 s94, s94, s86
	s_and_b32 s86, s94, 1
	s_lshr_b32 s94, s94, 1
	v_readlane_b32 s74, v248, 16
	v_readlane_b32 s75, v248, 17
	s_lshl_b32 s95, s94, 13
	s_lshl_b32 s80, s86, 12
	s_add_i32 s95, s95, s80
	s_add_i32 s95, s95, 0x8000000
	s_add_u32 s74, s74, s95
	s_addc_u32 s75, s75, 0
	s_lshl_b32 s95, s86, 23
	s_lshl_b32 s80, s94, 7
	s_add_i32 s95, s95, s80
	s_add_i32 s95, s95, 0x14000000
	s_add_u32 s76, s54, s95
	s_addc_u32 s77, s55, 0
	s_lshl_b32 s95, s94, 3
	s_lshl_b32 s80, s86, 2
	s_add_i32 s95, s95, s80
	s_add_i32 s95, s95, 0xe0000
	s_add_u32 s78, s54, s95
	s_addc_u32 s79, s55, 0
	s_branch .LBB0_784

.LBB0_786:
	s_add_i32 s10, s17, s1
	s_sub_i32 s24, 0x80, s10
	s_ashr_i32 s24, s24, 5
	s_cmpk_lt_u32 s10, 0x80
	v_lshl_add_u64 v[2:3], v[130:131], 0, s[10:11]
	s_cselect_b32 s24, s24, 0
	s_sub_i32 s10, 0x1060, s10
	s_ashr_i32 s10, s10, 5
	s_min_i32 s10, s10, 8
	v_lshlrev_b64 v[138:139], 11, v[2:3]
	s_waitcnt vmcnt(22)
	v_mov_b32_e32 v88, v170
	v_mov_b32_e32 v89, v171
	v_mov_b32_e32 v90, v172
	v_mov_b32_e32 v91, v173
	v_mov_b32_e32 v92, v174
	v_mov_b32_e32 v93, v175
	v_mov_b32_e32 v94, v176
	v_mov_b32_e32 v95, v177
	v_mov_b32_e32 v96, v178
	v_mov_b32_e32 v97, v179
	v_mov_b32_e32 v98, v180
	v_mov_b32_e32 v99, v181
	v_mov_b32_e32 v100, v182
	v_mov_b32_e32 v101, v183
	v_mov_b32_e32 v102, v184
	v_mov_b32_e32 v103, v185
	v_lshl_add_u64 v[186:187], v[138:139], 1, v[134:135]
	v_add_co_u32_e32 v186, vcc, 0x40000, v186
	s_nop 1
	v_addc_co_u32_e32 v187, vcc, 0, v187, vcc
	global_load_dwordx4 v[170:173], v[186:187], off
	global_load_dwordx4 v[174:177], v[186:187], off offset:32
	global_load_dwordx4 v[178:181], v[186:187], off offset:64
	global_load_dwordx4 v[182:185], v[186:187], off offset:96
	global_load_dwordx4 v[204:207], v249, s[74:75] offset:0 nt
	global_load_dwordx4 v[208:211], v249, s[74:75] offset:1024 nt
	global_load_dwordx4 v[212:215], v249, s[74:75] offset:2048 nt
	global_load_dwordx4 v[216:219], v249, s[74:75] offset:3072 nt
	s_add_u32 s74, s74, 0x800000
	s_addc_u32 s75, s75, 0
	global_load_dwordx4 v[220:223], v249, s[74:75] offset:0 nt
	global_load_dwordx4 v[224:227], v249, s[74:75] offset:1024 nt
	global_load_dwordx4 v[228:231], v249, s[74:75] offset:2048 nt
	global_load_dwordx4 v[232:235], v249, s[74:75] offset:3072 nt
	s_add_u32 s74, s74, 0x800000
	s_addc_u32 s75, s75, 0
	v_mov_b32_e32 v31, 0
	s_cmp_gt_i32 s24, s10
	v_mov_b32_e32 v30, 0
	v_mov_b32_e32 v29, 0
	v_mov_b32_e32 v28, 0
	v_mov_b32_e32 v27, 0
	v_mov_b32_e32 v26, 0
	v_mov_b32_e32 v25, 0
	v_mov_b32_e32 v24, 0
	v_mov_b32_e32 v23, 0
	v_mov_b32_e32 v22, 0
	v_mov_b32_e32 v21, 0
	v_mov_b32_e32 v20, 0
	v_mov_b32_e32 v19, 0
	v_mov_b32_e32 v18, 0
	v_mov_b32_e32 v17, 0
	v_mov_b32_e32 v16, 0
	v_mov_b32_e32 v47, 0
	v_mov_b32_e32 v46, 0
	v_mov_b32_e32 v45, 0
	v_mov_b32_e32 v44, 0
	v_mov_b32_e32 v43, 0
	v_mov_b32_e32 v42, 0
	v_mov_b32_e32 v41, 0
	v_mov_b32_e32 v40, 0
	v_mov_b32_e32 v39, 0
	v_mov_b32_e32 v38, 0
	v_mov_b32_e32 v37, 0
	v_mov_b32_e32 v36, 0
	v_mov_b32_e32 v35, 0
	v_mov_b32_e32 v34, 0
	v_mov_b32_e32 v33, 0
	v_mov_b32_e32 v32, 0
	v_mov_b32_e32 v148, v141
	s_cbranch_scc1 .LBB0_794
	v_mov_b32_e32 v14, v0
	v_mov_b32_e32 v15, v0
	v_mov_b32_e32 v1, v0
	v_mov_b32_e32 v2, v0
	v_mov_b32_e32 v3, v0
	v_mov_b32_e32 v4, v0
	v_mov_b32_e32 v5, v0
	v_mov_b32_e32 v6, v0
	v_mov_b32_e32 v7, v0
	v_mov_b32_e32 v8, v0
	v_mov_b32_e32 v9, v0
	v_mov_b32_e32 v10, v0
	v_mov_b32_e32 v11, v0
	v_mov_b32_e32 v12, v0
	v_mov_b32_e32 v13, v0
	v_mov_b64_e32 v[30:31], v[14:15]
	s_lshl_b32 s25, s24, 5
	s_mov_b32 s26, s16
	v_mov_b32_e32 v149, v146
	v_mov_b32_e32 v148, v141
	v_mov_b64_e32 v[28:29], v[12:13]
	v_mov_b64_e32 v[26:27], v[10:11]
	v_mov_b64_e32 v[24:25], v[8:9]
	v_mov_b64_e32 v[22:23], v[6:7]
	v_mov_b64_e32 v[20:21], v[4:5]
	v_mov_b64_e32 v[18:19], v[2:3]
	v_mov_b64_e32 v[16:17], v[0:1]
	v_mov_b32_e32 v150, v188
	v_mov_b64_e32 v[46:47], v[14:15]
	v_mov_b64_e32 v[44:45], v[12:13]
	v_mov_b64_e32 v[42:43], v[10:11]
	v_mov_b64_e32 v[40:41], v[8:9]
	v_mov_b64_e32 v[38:39], v[6:7]
	v_mov_b64_e32 v[36:37], v[4:5]
	v_mov_b64_e32 v[34:35], v[2:3]
	v_mov_b64_e32 v[32:33], v[0:1]

.LBB0_794:
	s_mov_b64 s[84:85], vcc
	s_waitcnt vmcnt(0)
	v_max3_f32 v236, |v204|, |v205|, |v206|
	v_max3_f32 v236, |v207|, |v208|, v236
	v_max3_f32 v236, |v209|, |v210|, v236
	v_max3_f32 v236, |v211|, |v212|, v236
	v_max3_f32 v236, |v213|, |v214|, v236
	v_max3_f32 v236, |v215|, |v216|, v236
	v_max3_f32 v236, |v217|, |v218|, v236
	v_max_f32_e64 v236, |v219|, v236
	s_nop 1
	v_mov_b32_dpp v237, v236 quad_perm:[1,0,3,2] row_mask:0xf bank_mask:0xf bound_ctrl:1
	v_max_f32_e32 v236, v236, v237
	s_nop 1
	v_mov_b32_dpp v237, v236 quad_perm:[2,3,0,1] row_mask:0xf bank_mask:0xf bound_ctrl:1
	v_max_f32_e32 v236, v236, v237
	s_nop 1
	v_mov_b32_dpp v237, v236 row_half_mirror row_mask:0xf bank_mask:0xf bound_ctrl:1
	v_max_f32_e32 v236, v236, v237
	s_nop 1
	v_mov_b32_dpp v237, v236 row_mirror row_mask:0xf bank_mask:0xf bound_ctrl:1
	v_max_f32_e32 v236, v236, v237
	v_mov_b32_e32 v237, v236
	s_nop 1
	v_permlane16_swap_b32_e32 v236, v237
	s_nop 1
	v_max_f32_e32 v236, v236, v237
	v_mov_b32_e32 v237, v236
	s_nop 1
	v_permlane32_swap_b32_e32 v236, v237
	s_nop 1
	v_max_f32_e32 v236, v236, v237
	v_max_f32_e32 v236, 0xda24260, v236
	v_mul_f32_e32 v238, 0x3e2aaaab, v236
	global_store_dword v252, v238, s[78:79]
	v_div_scale_f32 v239, s[82:83], v238, v238, 1.0
	v_rcp_f32_e32 v240, v239
	v_div_scale_f32 v241, vcc, 1.0, v238, 1.0
	v_fma_f32 v242, -v239, v240, 1.0
	v_fmac_f32_e32 v240, v242, v240
	v_mul_f32_e32 v242, v241, v240
	v_fma_f32 v243, -v239, v242, v241
	v_fmac_f32_e32 v242, v243, v240
	v_fma_f32 v239, -v239, v242, v241
	s_nop 0
	v_div_fmas_f32 v239, v239, v240, v242
	v_div_fixup_f32 v244, v239, v238, 1.0
	v_mul_f32_e32 v204, v244, v204
	v_mul_f32_e32 v205, v244, v205
	v_mul_f32_e32 v206, v244, v206
	v_mul_f32_e32 v207, v244, v207
	v_mul_f32_e32 v208, v244, v208
	v_mul_f32_e32 v209, v244, v209
	v_mul_f32_e32 v210, v244, v210
	v_mul_f32_e32 v211, v244, v211
	v_mul_f32_e32 v212, v244, v212
	v_mul_f32_e32 v213, v244, v213
	v_mul_f32_e32 v214, v244, v214
	v_mul_f32_e32 v215, v244, v215
	v_mul_f32_e32 v216, v244, v216
	v_mul_f32_e32 v217, v244, v217
	v_mul_f32_e32 v218, v244, v218
	v_mul_f32_e32 v219, v244, v219
	v_mov_b32_e32 v245, 0
	v_mov_b32_e32 v246, 0
	v_mov_b32_e32 v247, 0
	v_mov_b32_e32 v237, 0
	v_cvt_scalef32_pk_fp4_f32 v245, v204, v205, 1.0
	v_cvt_scalef32_pk_fp4_f32 v246, v208, v209, 1.0
	v_cvt_scalef32_pk_fp4_f32 v247, v212, v213, 1.0
	v_cvt_scalef32_pk_fp4_f32 v237, v216, v217, 1.0
	v_cvt_scalef32_pk_fp4_f32 v245, v206, v207, 1.0 op_sel:[0,0,1,0]
	v_cvt_scalef32_pk_fp4_f32 v246, v210, v211, 1.0 op_sel:[0,0,1,0]
	v_cvt_scalef32_pk_fp4_f32 v247, v214, v215, 1.0 op_sel:[0,0,1,0]
	v_cvt_scalef32_pk_fp4_f32 v237, v218, v219, 1.0 op_sel:[0,0,1,0]
	v_mov_b32_dpp v204, v245 quad_perm:[0,0,0,0] row_mask:0xf bank_mask:0xf bound_ctrl:1
	v_mov_b32_dpp v208, v246 quad_perm:[0,0,0,0] row_mask:0xf bank_mask:0xf bound_ctrl:1
	v_mov_b32_dpp v212, v247 quad_perm:[0,0,0,0] row_mask:0xf bank_mask:0xf bound_ctrl:1
	v_mov_b32_dpp v216, v237 quad_perm:[0,0,0,0] row_mask:0xf bank_mask:0xf bound_ctrl:1
	v_mov_b32_dpp v205, v245 quad_perm:[1,1,1,1] row_mask:0xf bank_mask:0xf bound_ctrl:1
	v_mov_b32_dpp v209, v246 quad_perm:[1,1,1,1] row_mask:0xf bank_mask:0xf bound_ctrl:1
	v_mov_b32_dpp v213, v247 quad_perm:[1,1,1,1] row_mask:0xf bank_mask:0xf bound_ctrl:1
	v_mov_b32_dpp v217, v237 quad_perm:[1,1,1,1] row_mask:0xf bank_mask:0xf bound_ctrl:1
	v_mov_b32_dpp v206, v245 quad_perm:[2,2,2,2] row_mask:0xf bank_mask:0xf bound_ctrl:1
	v_mov_b32_dpp v210, v246 quad_perm:[2,2,2,2] row_mask:0xf bank_mask:0xf bound_ctrl:1
	v_mov_b32_dpp v214, v247 quad_perm:[2,2,2,2] row_mask:0xf bank_mask:0xf bound_ctrl:1
	v_mov_b32_dpp v218, v237 quad_perm:[2,2,2,2] row_mask:0xf bank_mask:0xf bound_ctrl:1
	v_mov_b32_dpp v207, v245 quad_perm:[3,3,3,3] row_mask:0xf bank_mask:0xf bound_ctrl:1
	v_mov_b32_dpp v211, v246 quad_perm:[3,3,3,3] row_mask:0xf bank_mask:0xf bound_ctrl:1
	v_mov_b32_dpp v215, v247 quad_perm:[3,3,3,3] row_mask:0xf bank_mask:0xf bound_ctrl:1
	v_mov_b32_dpp v219, v237 quad_perm:[3,3,3,3] row_mask:0xf bank_mask:0xf bound_ctrl:1
	v_bfe_u32 v204, v204, v251, 4
	v_bfe_u32 v208, v208, v251, 4
	v_bfe_u32 v212, v212, v251, 4
	v_bfe_u32 v216, v216, v251, 4
	v_bfe_u32 v205, v205, v251, 4
	v_bfe_u32 v209, v209, v251, 4
	v_bfe_u32 v213, v213, v251, 4
	v_bfe_u32 v217, v217, v251, 4
	v_bfe_u32 v206, v206, v251, 4
	v_bfe_u32 v210, v210, v251, 4
	v_bfe_u32 v214, v214, v251, 4
	v_bfe_u32 v218, v218, v251, 4
	v_bfe_u32 v207, v207, v251, 4
	v_bfe_u32 v211, v211, v251, 4
	v_bfe_u32 v215, v215, v251, 4
	v_bfe_u32 v219, v219, v251, 4
	v_lshl_or_b32 v204, v205, 4, v204
	v_lshl_or_b32 v208, v209, 4, v208
	v_lshl_or_b32 v212, v213, 4, v212
	v_lshl_or_b32 v216, v217, 4, v216
	v_lshl_or_b32 v204, v206, 8, v204
	v_lshl_or_b32 v208, v210, 8, v208
	v_lshl_or_b32 v212, v214, 8, v212
	v_lshl_or_b32 v216, v218, 8, v216
	v_lshl_or_b32 v204, v207, 12, v204
	v_lshl_or_b32 v208, v211, 12, v208
	v_lshl_or_b32 v212, v215, 12, v212
	v_lshl_or_b32 v216, v219, 12, v216
	v_mov_b32_dpp v205, v204 row_shr:4 row_mask:0xf bank_mask:0xf bound_ctrl:1
	v_mov_b32_dpp v209, v208 row_shr:4 row_mask:0xf bank_mask:0xf bound_ctrl:1
	v_mov_b32_dpp v213, v212 row_shr:4 row_mask:0xf bank_mask:0xf bound_ctrl:1
	v_mov_b32_dpp v217, v216 row_shr:4 row_mask:0xf bank_mask:0xf bound_ctrl:1
	v_lshl_or_b32 v204, v204, 16, v205
	v_lshl_or_b32 v208, v208, 16, v209
	v_lshl_or_b32 v212, v212, 16, v213
	v_lshl_or_b32 v216, v216, 16, v217
	s_mov_b32 vcc_lo, 0xf0f0f0f0
	s_mov_b32 vcc_hi, 0xf0f0f0f0
	s_mov_b64 exec, vcc
	global_store_dword v250, v204, s[76:77] nt
	s_add_u32 s80, s76, 0x200000
	s_addc_u32 s81, s77, 0
	global_store_dword v250, v208, s[80:81] nt
	s_add_u32 s80, s76, 0x400000
	s_addc_u32 s81, s77, 0
	global_store_dword v250, v212, s[80:81] nt
	s_add_u32 s80, s76, 0x600000
	s_addc_u32 s81, s77, 0
	global_store_dword v250, v216, s[80:81] nt
	s_mov_b64 exec, -1
	s_add_u32 s76, s76, 0x20000
	s_addc_u32 s77, s77, 0
	s_add_u32 s78, s78, 0x2000
	s_addc_u32 s79, s79, 0
	v_max3_f32 v236, |v220|, |v221|, |v222|
	v_max3_f32 v236, |v223|, |v224|, v236
	v_max3_f32 v236, |v225|, |v226|, v236
	v_max3_f32 v236, |v227|, |v228|, v236
	v_max3_f32 v236, |v229|, |v230|, v236
	v_max3_f32 v236, |v231|, |v232|, v236
	v_max3_f32 v236, |v233|, |v234|, v236
	v_max_f32_e64 v236, |v235|, v236
	s_nop 1
	v_mov_b32_dpp v237, v236 quad_perm:[1,0,3,2] row_mask:0xf bank_mask:0xf bound_ctrl:1
	v_max_f32_e32 v236, v236, v237
	s_nop 1
	v_mov_b32_dpp v237, v236 quad_perm:[2,3,0,1] row_mask:0xf bank_mask:0xf bound_ctrl:1
	v_max_f32_e32 v236, v236, v237
	s_nop 1
	v_mov_b32_dpp v237, v236 row_half_mirror row_mask:0xf bank_mask:0xf bound_ctrl:1
	v_max_f32_e32 v236, v236, v237
	s_nop 1
	v_mov_b32_dpp v237, v236 row_mirror row_mask:0xf bank_mask:0xf bound_ctrl:1
	v_max_f32_e32 v236, v236, v237
	v_mov_b32_e32 v237, v236
	s_nop 1
	v_permlane16_swap_b32_e32 v236, v237
	s_nop 1
	v_max_f32_e32 v236, v236, v237
	v_mov_b32_e32 v237, v236
	s_nop 1
	v_permlane32_swap_b32_e32 v236, v237
	s_nop 1
	v_max_f32_e32 v236, v236, v237
	v_max_f32_e32 v236, 0xda24260, v236
	v_mul_f32_e32 v238, 0x3e2aaaab, v236
	global_store_dword v252, v238, s[78:79]
	v_div_scale_f32 v239, s[82:83], v238, v238, 1.0
	v_rcp_f32_e32 v240, v239
	v_div_scale_f32 v241, vcc, 1.0, v238, 1.0
	v_fma_f32 v242, -v239, v240, 1.0
	v_fmac_f32_e32 v240, v242, v240
	v_mul_f32_e32 v242, v241, v240
	v_fma_f32 v243, -v239, v242, v241
	v_fmac_f32_e32 v242, v243, v240
	v_fma_f32 v239, -v239, v242, v241
	s_nop 0
	v_div_fmas_f32 v239, v239, v240, v242
	v_div_fixup_f32 v244, v239, v238, 1.0
	v_mul_f32_e32 v220, v244, v220
	v_mul_f32_e32 v221, v244, v221
	v_mul_f32_e32 v222, v244, v222
	v_mul_f32_e32 v223, v244, v223
	v_mul_f32_e32 v224, v244, v224
	v_mul_f32_e32 v225, v244, v225
	v_mul_f32_e32 v226, v244, v226
	v_mul_f32_e32 v227, v244, v227
	v_mul_f32_e32 v228, v244, v228
	v_mul_f32_e32 v229, v244, v229
	v_mul_f32_e32 v230, v244, v230
	v_mul_f32_e32 v231, v244, v231
	v_mul_f32_e32 v232, v244, v232
	v_mul_f32_e32 v233, v244, v233
	v_mul_f32_e32 v234, v244, v234
	v_mul_f32_e32 v235, v244, v235
	v_mov_b32_e32 v245, 0
	v_mov_b32_e32 v246, 0
	v_mov_b32_e32 v247, 0
	v_mov_b32_e32 v237, 0
	v_cvt_scalef32_pk_fp4_f32 v245, v220, v221, 1.0
	v_cvt_scalef32_pk_fp4_f32 v246, v224, v225, 1.0
	v_cvt_scalef32_pk_fp4_f32 v247, v228, v229, 1.0
	v_cvt_scalef32_pk_fp4_f32 v237, v232, v233, 1.0
	v_cvt_scalef32_pk_fp4_f32 v245, v222, v223, 1.0 op_sel:[0,0,1,0]
	v_cvt_scalef32_pk_fp4_f32 v246, v226, v227, 1.0 op_sel:[0,0,1,0]
	v_cvt_scalef32_pk_fp4_f32 v247, v230, v231, 1.0 op_sel:[0,0,1,0]
	v_cvt_scalef32_pk_fp4_f32 v237, v234, v235, 1.0 op_sel:[0,0,1,0]
	v_mov_b32_dpp v220, v245 quad_perm:[0,0,0,0] row_mask:0xf bank_mask:0xf bound_ctrl:1
	v_mov_b32_dpp v224, v246 quad_perm:[0,0,0,0] row_mask:0xf bank_mask:0xf bound_ctrl:1
	v_mov_b32_dpp v228, v247 quad_perm:[0,0,0,0] row_mask:0xf bank_mask:0xf bound_ctrl:1
	v_mov_b32_dpp v232, v237 quad_perm:[0,0,0,0] row_mask:0xf bank_mask:0xf bound_ctrl:1
	v_mov_b32_dpp v221, v245 quad_perm:[1,1,1,1] row_mask:0xf bank_mask:0xf bound_ctrl:1
	v_mov_b32_dpp v225, v246 quad_perm:[1,1,1,1] row_mask:0xf bank_mask:0xf bound_ctrl:1
	v_mov_b32_dpp v229, v247 quad_perm:[1,1,1,1] row_mask:0xf bank_mask:0xf bound_ctrl:1
	v_mov_b32_dpp v233, v237 quad_perm:[1,1,1,1] row_mask:0xf bank_mask:0xf bound_ctrl:1
	v_mov_b32_dpp v222, v245 quad_perm:[2,2,2,2] row_mask:0xf bank_mask:0xf bound_ctrl:1
	v_mov_b32_dpp v226, v246 quad_perm:[2,2,2,2] row_mask:0xf bank_mask:0xf bound_ctrl:1
	v_mov_b32_dpp v230, v247 quad_perm:[2,2,2,2] row_mask:0xf bank_mask:0xf bound_ctrl:1
	v_mov_b32_dpp v234, v237 quad_perm:[2,2,2,2] row_mask:0xf bank_mask:0xf bound_ctrl:1
	v_mov_b32_dpp v223, v245 quad_perm:[3,3,3,3] row_mask:0xf bank_mask:0xf bound_ctrl:1
	v_mov_b32_dpp v227, v246 quad_perm:[3,3,3,3] row_mask:0xf bank_mask:0xf bound_ctrl:1
	v_mov_b32_dpp v231, v247 quad_perm:[3,3,3,3] row_mask:0xf bank_mask:0xf bound_ctrl:1
	v_mov_b32_dpp v235, v237 quad_perm:[3,3,3,3] row_mask:0xf bank_mask:0xf bound_ctrl:1
	v_bfe_u32 v220, v220, v251, 4
	v_bfe_u32 v224, v224, v251, 4
	v_bfe_u32 v228, v228, v251, 4
	v_bfe_u32 v232, v232, v251, 4
	v_bfe_u32 v221, v221, v251, 4
	v_bfe_u32 v225, v225, v251, 4
	v_bfe_u32 v229, v229, v251, 4
	v_bfe_u32 v233, v233, v251, 4
	v_bfe_u32 v222, v222, v251, 4
	v_bfe_u32 v226, v226, v251, 4
	v_bfe_u32 v230, v230, v251, 4
	v_bfe_u32 v234, v234, v251, 4
	v_bfe_u32 v223, v223, v251, 4
	v_bfe_u32 v227, v227, v251, 4
	v_bfe_u32 v231, v231, v251, 4
	v_bfe_u32 v235, v235, v251, 4
	v_lshl_or_b32 v220, v221, 4, v220
	v_lshl_or_b32 v224, v225, 4, v224
	v_lshl_or_b32 v228, v229, 4, v228
	v_lshl_or_b32 v232, v233, 4, v232
	v_lshl_or_b32 v220, v222, 8, v220
	v_lshl_or_b32 v224, v226, 8, v224
	v_lshl_or_b32 v228, v230, 8, v228
	v_lshl_or_b32 v232, v234, 8, v232
	v_lshl_or_b32 v220, v223, 12, v220
	v_lshl_or_b32 v224, v227, 12, v224
	v_lshl_or_b32 v228, v231, 12, v228
	v_lshl_or_b32 v232, v235, 12, v232
	v_mov_b32_dpp v221, v220 row_shr:4 row_mask:0xf bank_mask:0xf bound_ctrl:1
	v_mov_b32_dpp v225, v224 row_shr:4 row_mask:0xf bank_mask:0xf bound_ctrl:1
	v_mov_b32_dpp v229, v228 row_shr:4 row_mask:0xf bank_mask:0xf bound_ctrl:1
	v_mov_b32_dpp v233, v232 row_shr:4 row_mask:0xf bank_mask:0xf bound_ctrl:1
	v_lshl_or_b32 v220, v220, 16, v221
	v_lshl_or_b32 v224, v224, 16, v225
	v_lshl_or_b32 v228, v228, 16, v229
	v_lshl_or_b32 v232, v232, 16, v233
	s_mov_b32 vcc_lo, 0xf0f0f0f0
	s_mov_b32 vcc_hi, 0xf0f0f0f0
	s_mov_b64 exec, vcc
	global_store_dword v250, v220, s[76:77] nt
	s_add_u32 s80, s76, 0x200000
	s_addc_u32 s81, s77, 0
	global_store_dword v250, v224, s[80:81] nt
	s_add_u32 s80, s76, 0x400000
	s_addc_u32 s81, s77, 0
	global_store_dword v250, v228, s[80:81] nt
	s_add_u32 s80, s76, 0x600000
	s_addc_u32 s81, s77, 0
	global_store_dword v250, v232, s[80:81] nt
	s_mov_b64 exec, -1
	s_add_u32 s76, s76, 0x20000
	s_addc_u32 s77, s77, 0
	s_add_u32 s78, s78, 0x2000
	s_addc_u32 s79, s79, 0
	s_mov_b64 vcc, s[84:85]
	v_mov_b32_e32 v1, v148
	s_nop 1
	v_permlane32_swap_b32_e32 v148, v1
	v_add_f32_e32 v1, v148, v1
	v_div_scale_f32 v2, s[24:25], v1, v1, 1.0
	v_rcp_f32_e32 v3, v2
	s_nop 0
	v_fma_f32 v4, -v2, v3, 1.0
	v_fmac_f32_e32 v3, v4, v3
	v_div_scale_f32 v4, vcc, 1.0, v1, 1.0
	v_mul_f32_e32 v5, v4, v3
	v_fma_f32 v6, -v2, v5, v4
	v_fmac_f32_e32 v5, v6, v3
	v_fma_f32 v2, -v2, v5, v4
	v_div_fmas_f32 v2, v2, v3, v5
	v_div_fixup_f32 v1, v2, v1, 1.0
	v_mul_f32_e32 v4, v16, v1
	v_mul_f32_e32 v5, v17, v1
	v_cvt_pk_bf16_f32 v204, v4, v5
	v_mul_f32_e32 v4, v18, v1
	v_mul_f32_e32 v5, v19, v1
	v_cvt_pk_bf16_f32 v205, v4, v5
	v_mul_f32_e32 v4, v20, v1
	v_mul_f32_e32 v5, v21, v1
	v_cvt_pk_bf16_f32 v208, v4, v5
	v_mul_f32_e32 v4, v22, v1
	v_mul_f32_e32 v5, v23, v1
	v_cvt_pk_bf16_f32 v209, v4, v5
	v_mul_f32_e32 v4, v24, v1
	v_mul_f32_e32 v5, v25, v1
	v_cvt_pk_bf16_f32 v206, v4, v5
	v_mul_f32_e32 v4, v26, v1
	v_mul_f32_e32 v5, v27, v1
	v_cvt_pk_bf16_f32 v207, v4, v5
	v_mul_f32_e32 v4, v28, v1
	v_mul_f32_e32 v5, v29, v1
	v_cvt_pk_bf16_f32 v210, v4, v5
	v_mul_f32_e32 v4, v30, v1
	v_mul_f32_e32 v5, v31, v1
	v_cvt_pk_bf16_f32 v211, v4, v5
	v_mul_f32_e32 v4, v32, v1
	v_mul_f32_e32 v5, v33, v1
	v_cvt_pk_bf16_f32 v212, v4, v5
	v_mul_f32_e32 v4, v34, v1
	v_mul_f32_e32 v5, v35, v1
	v_cvt_pk_bf16_f32 v213, v4, v5
	v_mul_f32_e32 v4, v36, v1
	v_mul_f32_e32 v5, v37, v1
	v_cvt_pk_bf16_f32 v216, v4, v5
	v_mul_f32_e32 v4, v38, v1
	v_mul_f32_e32 v5, v39, v1
	v_cvt_pk_bf16_f32 v217, v4, v5
	v_mul_f32_e32 v4, v40, v1
	v_mul_f32_e32 v5, v41, v1
	v_cvt_pk_bf16_f32 v214, v4, v5
	v_mul_f32_e32 v4, v42, v1
	v_mul_f32_e32 v5, v43, v1
	v_cvt_pk_bf16_f32 v215, v4, v5
	v_mul_f32_e32 v4, v44, v1
	v_mul_f32_e32 v5, v45, v1
	v_cvt_pk_bf16_f32 v218, v4, v5
	v_mul_f32_e32 v4, v46, v1
	v_mul_f32_e32 v5, v47, v1
	v_cvt_pk_bf16_f32 v219, v4, v5
	v_lshl_add_u64 v[2:3], v[138:139], 1, v[136:137]
	v_lshl_add_u64 v[2:3], v[254:255], 0, v[2:3]
	s_nop 0
	v_permlane32_swap_b32_e32 v204, v206
	v_permlane32_swap_b32_e32 v205, v207
	v_permlane32_swap_b32_e32 v208, v210
	v_permlane32_swap_b32_e32 v209, v211
	v_permlane32_swap_b32_e32 v212, v214
	v_permlane32_swap_b32_e32 v213, v215
	v_permlane32_swap_b32_e32 v216, v218
	v_permlane32_swap_b32_e32 v217, v219
	s_and_b64 vcc, exec, s[4:5]
	global_store_dwordx4 v[2:3], v[204:207], off
	global_store_dwordx4 v[2:3], v[208:211], off offset:16
	global_store_dwordx4 v[2:3], v[212:215], off offset:64
	global_store_dwordx4 v[2:3], v[216:219], off offset:80
	s_cbranch_vccnz .LBB0_783
	s_addk_i32 s17, 0x240
	s_and_b32 s4, s17, 0xffff
	s_mul_i32 s4, s4, 0xaaab
	s_lshr_b32 s4, s4, 24
	s_mulk_i32 s4, 0x180
	s_sub_i32 s4, s17, s4
	s_and_b32 s4, s4, 0xffff
	v_add_u32_e32 v1, s4, v108
	v_lshlrev_b32_e32 v2, 7, v1
	v_lshrrev_b32_e32 v1, 1, v1
	v_xor_b32_e32 v1, v1, v115
	v_lshlrev_b32_e32 v1, 4, v1
	v_and_b32_e32 v1, 0x70, v1
	v_add3_u32 v1, 0, v2, v1
	s_waitcnt vmcnt(19)
	ds_write_b128 v1, v[80:83]
	v_or_b32_e32 v1, s4, v110
	v_lshlrev_b32_e32 v1, 1, v1
	v_add3_u32 v1, v121, v1, s21
	s_waitcnt vmcnt(18)
	ds_write2_b64 v1, v[84:85], v[86:87] offset1:1
	s_branch .LBB0_783
